# attention unit prologues: the zeroing of the K/V tile staging registers also moves ahead of the prologue barrier (after their LDS writes); only three v_mov remain after the barrier
# baseline (speedup 1.0000x reference)
.LBB0_514:
	v_readfirstlane_b32 s67, v183
	s_ashr_i32 s69, s67, 6
	s_lshl_b32 s24, s69, 5
	s_and_b32 s65, s24, 0xe0
	v_or_b32_e32 v0, s65, v203
	s_ashr_i32 s24, s67, 9
	v_mul_u32_u24_e32 v0, 0x1800, v0
	v_lshl_add_u64 v[2:3], s[22:23], 0, v[0:1]
	s_mul_i32 s22, s24, 0xc0
	s_ashr_i32 s23, s22, 31
	v_lshl_add_u64 v[2:3], s[22:23], 1, v[2:3]
	v_lshlrev_b32_e32 v0, 1, v182
	v_lshl_add_u64 v[2:3], v[2:3], 0, v[0:1]
	global_load_dwordx4 v[98:101], v[2:3], off
	global_load_dwordx4 v[102:105], v[2:3], off offset:32
	global_load_dwordx4 v[106:109], v[2:3], off offset:64
	global_load_dwordx4 v[110:113], v[2:3], off offset:96
	global_load_dwordx4 v[114:117], v[2:3], off offset:128
	global_load_dwordx4 v[118:121], v[2:3], off offset:160
	global_load_dwordx4 v[122:125], v[2:3], off offset:192
	global_load_dwordx4 v[126:129], v[2:3], off offset:224
	global_load_dwordx4 v[130:133], v[2:3], off offset:256
	global_load_dwordx4 v[134:137], v[2:3], off offset:288
	global_load_dwordx4 v[138:141], v[2:3], off offset:320
	global_load_dwordx4 v[142:145], v[2:3], off offset:352
	v_lshl_add_u64 v[2:3], s[16:17], 0, v[184:185]
	global_load_dwordx4 v[2:5], v[2:3], off
	v_lshl_add_u64 v[6:7], s[16:17], 0, v[186:187]
	global_load_dwordx4 v[6:9], v[6:7], off
	v_lshl_add_u64 v[10:11], s[18:19], 0, v[188:189]
	v_lshl_add_u64 v[14:15], s[20:21], 0, v[184:185]
	global_load_dwordx4 v[10:13], v[10:11], off
	v_lshl_add_u64 v[18:19], s[20:21], 0, v[186:187]
	global_load_dwordx4 v[14:17], v[14:15], off
	v_lshl_add_u64 v[22:23], s[16:17], 0, v[190:191]
	global_load_dwordx4 v[18:21], v[18:19], off
	v_lshl_add_u64 v[26:27], s[16:17], 0, v[192:193]
	global_load_dwordx4 v[22:25], v[22:23], off
	v_lshl_add_u64 v[30:31], s[18:19], 0, v[222:223]
	global_load_dwordx4 v[26:29], v[26:27], off
	v_lshl_add_u64 v[34:35], s[20:21], 0, v[190:191]
	global_load_dwordx4 v[30:33], v[30:31], off
	v_lshl_add_u64 v[38:39], s[20:21], 0, v[192:193]
	global_load_dwordx4 v[34:37], v[34:35], off
	v_add_u32_e32 v0, v202, v218
	global_load_dwordx4 v[38:41], v[38:39], off
	s_and_b32 s22, s67, 0xffffff00
	s_cmpk_eq_i32 s22, 0x100
	s_cselect_b64 s[24:25], -1, 0
	s_cmpk_lg_i32 s22, 0x100
	s_cselect_b64 s[26:27], -1, 0
	v_mov_b64_e32 v[236:237], 0xff
	s_and_b64 vcc, exec, s[26:27]
	v_mov_b32_e32 v42, v1
	v_mov_b32_e32 v43, v1
	v_mov_b32_e32 v44, v1
	v_mov_b32_e32 v45, v1
	v_mov_b32_e32 v46, v1
	v_mov_b32_e32 v47, v1
	v_mov_b32_e32 v48, v1
	v_mov_b32_e32 v49, v1
	v_mov_b32_e32 v50, v1
	v_mov_b32_e32 v51, v1
	v_mov_b32_e32 v52, v1
	v_mov_b32_e32 v53, v1
	v_mov_b32_e32 v54, v1
	v_mov_b32_e32 v55, v1
	v_mov_b32_e32 v56, v1
	v_mov_b32_e32 v57, v1
	v_mov_b32_e32 v58, v1
	v_mov_b32_e32 v59, v1
	v_mov_b32_e32 v60, v1
	v_mov_b32_e32 v61, v1
	v_mov_b32_e32 v62, v1
	v_mov_b32_e32 v63, v1
	v_mov_b32_e32 v64, v1
	v_mov_b32_e32 v65, v1
	v_mov_b32_e32 v66, v1
	v_mov_b32_e32 v67, v1
	v_mov_b32_e32 v68, v1
	v_mov_b32_e32 v69, v1
	v_mov_b32_e32 v70, v1
	v_mov_b32_e32 v71, v1
	v_mov_b32_e32 v72, v1
	v_mov_b32_e32 v73, v1
	v_mov_b32_e32 v74, v1
	v_mov_b32_e32 v75, v1
	v_mov_b32_e32 v76, v1
	v_mov_b32_e32 v77, v1
	v_mov_b32_e32 v78, v1
	v_mov_b32_e32 v79, v1
	v_mov_b32_e32 v80, v1
	v_mov_b32_e32 v81, v1
	v_mov_b32_e32 v82, v1
	v_mov_b32_e32 v83, v1
	v_mov_b32_e32 v84, v1
	v_mov_b32_e32 v85, v1
	v_mov_b32_e32 v86, v1
	v_mov_b32_e32 v87, v1
	v_mov_b32_e32 v88, v1
	v_mov_b32_e32 v89, v1
	v_mov_b32_e32 v90, v1
	v_mov_b32_e32 v91, v1
	v_mov_b32_e32 v92, v1
	v_mov_b32_e32 v93, v1
	v_mov_b32_e32 v94, v1
	v_mov_b32_e32 v95, v1
	v_mov_b32_e32 v96, v1
	v_mov_b32_e32 v97, v1
	v_mov_b32_e32 v239, v1
	v_mov_b32_e32 v240, v1
	s_waitcnt vmcnt(0)
	ds_write_b128 v0, v[2:5]
	v_add_u32_e32 v0, v198, v220
	ds_write_b128 v0, v[6:9]
	ds_write_b128 v234, v[10:13] offset:256
	v_add_u32_e32 v0, v200, v218
	v_lshl_add_u64 v[2:3], s[16:17], 0, v[210:211]
	ds_write_b128 v0, v[14:17] offset:25600
	v_add_u32_e32 v0, v208, v220
	ds_write_b128 v0, v[18:21] offset:25600
	ds_write_b128 v235, v[22:25] offset:46080
	ds_write_b128 v224, v[26:29] offset:46080
	ds_write_b128 v234, v[30:33] offset:46336
	ds_write_b128 v254, v[34:37]
	ds_write_b128 v238, v[38:41]
	global_load_dwordx4 v[146:149], v[2:3], off
	v_lshl_add_u64 v[2:3], s[16:17], 0, v[212:213]
	global_load_dwordx4 v[150:153], v[2:3], off
	v_lshl_add_u64 v[2:3], s[18:19], 0, v[214:215]
	global_load_dwordx4 v[154:157], v[2:3], off
	v_lshl_add_u64 v[2:3], s[20:21], 0, v[210:211]
	global_load_dwordx4 v[158:161], v[2:3], off
	v_lshl_add_u64 v[2:3], s[20:21], 0, v[212:213]
	global_load_dwordx4 v[162:165], v[2:3], off
	v_mov_b32_e32 v4, v1
	v_mov_b32_e32 v5, v1
	v_mov_b32_e32 v6, v1
	v_mov_b32_e32 v7, v1
	v_mov_b32_e32 v8, v1
	v_mov_b32_e32 v9, v1
	v_mov_b32_e32 v10, v1
	v_mov_b32_e32 v11, v1
	v_mov_b32_e32 v12, v1
	v_mov_b32_e32 v13, v1
	v_mov_b32_e32 v14, v1
	v_mov_b32_e32 v15, v1
	v_mov_b32_e32 v16, v1
	v_mov_b32_e32 v17, v1
	v_mov_b32_e32 v18, v1
	v_mov_b32_e32 v19, v1
	v_mov_b32_e32 v20, v1
	v_mov_b32_e32 v21, v1
	v_mov_b32_e32 v22, v1
	v_mov_b32_e32 v23, v1
	v_mov_b32_e32 v24, v1
	v_mov_b32_e32 v25, v1
	v_mov_b32_e32 v26, v1
	v_mov_b32_e32 v27, v1
	v_mov_b32_e32 v28, v1
	v_mov_b32_e32 v29, v1
	v_mov_b32_e32 v30, v1
	v_mov_b32_e32 v31, v1
	v_mov_b32_e32 v32, v1
	v_mov_b32_e32 v33, v1
	v_mov_b32_e32 v34, v1
	v_mov_b32_e32 v35, v1
	v_mov_b32_e32 v36, v1
	v_mov_b32_e32 v37, v1
	v_mov_b32_e32 v38, v1
	v_mov_b32_e32 v39, v1
	v_mov_b32_e32 v40, v1
	v_mov_b32_e32 v41, v1
	s_waitcnt lgkmcnt(0)
	s_barrier
	s_cbranch_vccnz .LBB0_516
	s_setprio 1
.LBB0_516:
	s_add_i32 s70, s68, s28
	s_lshl_b32 s30, s70, 1
	s_cmp_gt_u32 s69, 3
	s_cselect_b64 s[28:29], -1, 0
	v_cndmask_b32_e64 v0, 0, 1, s[28:29]
	v_or_b32_e32 v217, s30, v0
	v_mov_b32_e32 v0, v1
	v_mov_b32_e32 v2, v1
	v_mov_b32_e32 v3, v1
	s_cmp_lt_u32 s69, 4
	s_cselect_b64 s[22:23], -1, 0
	s_mov_b32 s71, 0
	s_cmp_gt_u32 s69, 3
	s_cselect_b32 s100, 1, 0
	s_cselect_b32 s99, -1, 0
	s_mov_b32 s98, 0
	s_branch .LBB0_518

.LBB0_790:
	v_mov_b32_e32 v4, v1
	v_mov_b32_e32 v5, v1
	v_mov_b32_e32 v6, v1
	v_mov_b32_e32 v7, v1
	v_mov_b32_e32 v8, v1
	v_mov_b32_e32 v9, v1
	v_mov_b32_e32 v10, v1
	v_mov_b32_e32 v11, v1
	s_and_b32 s18, s69, 0xffffff00
	s_cmpk_eq_i32 s18, 0x100
	s_cselect_b64 s[22:23], -1, 0
	s_cmpk_lg_i32 s18, 0x100
	s_cselect_b64 s[24:25], -1, 0
	s_and_b64 vcc, exec, s[24:25]
	s_waitcnt lgkmcnt(0)
	s_barrier
	s_cbranch_vccnz .LBB0_792
	s_setprio 1
.LBB0_792:
	s_lshl_b32 s29, s72, 1
	s_cmp_gt_u32 s71, 3
	s_cselect_b64 s[26:27], -1, 0
	v_cndmask_b32_e64 v0, 0, 1, s[26:27]
	s_cmp_lt_u32 s71, 4
	v_readfirstlane_b32 s30, v0
	s_cselect_b64 s[18:19], -1, 0
	s_or_b32 s73, s29, s30
	s_cmp_lt_i32 s73, 1
	s_cbranch_scc1 .LBB0_815
	v_or_b32_e32 v0, s28, v2
	v_sub_u32_e32 v135, v124, v0
	v_mov_b32_e32 v0, v1
	v_mov_b32_e32 v2, v1
	s_mov_b32 s77, 0
	s_cmp_gt_u32 s71, 3
	s_cselect_b32 s100, 1, 0
	s_cselect_b32 s99, -1, 0
	s_mov_b32 s98, 0
	s_branch .LBB0_795
